# split-phase barrier 5 re-done on the LIVE P5 K-loop (.LBB0_888; the earlier version hooked the G<256 variant and never waited); dead-variant p5res dropped; passes the P4-lateness stress test
# speedup vs baseline: 1.0272x; 1.0272x over previous
; __device__ __forceinline__ unsigned xb_ld(unsigned* p)              { return __hip_atomic_load(p, __ATOMIC_RELAXED, __HIP_MEMORY_SCOPE_AGENT); }
; __device__ __forceinline__ unsigned xb_add(unsigned* p, unsigned v) { return __hip_atomic_fetch_add(p, v, __ATOMIC_RELAXED, __HIP_MEMORY_SCOPE_AGENT); }
; #define XB_SPIN(cond, bar) do { unsigned _sp = 0; while (cond) { __builtin_amdgcn_s_sleep(1); \
;     if ((++_sp & 255u) == 0u) { if (xb_ld(&(bar)[XB_TMO])) break; if (_sp > XB_SPIN_CAP) { atomicAdd(&(bar)[XB_TMO], 1u); break; } } } } while (0)
; __device__ __forceinline__ void xcd_barrier(const XcdBarrier& b) {
;     ...
;             else XB_SPIN(xb_ld(&bar[XB_TOPGEN]) == tg, bar);
;             __builtin_amdgcn_fence(__ATOMIC_ACQUIRE, "agent");
;             xb_add(&bar[XB_XGEN(b.x)], 1u);
;             asm volatile("s_waitcnt vmcnt(0)" ::: "memory");
;         } else {
;             XB_SPIN(xb_ld(&bar[XB_XGEN(b.x)]) == gen, bar);
;             __builtin_amdgcn_fence(__ATOMIC_ACQUIRE, "agent");
;             asm volatile("s_waitcnt vmcnt(0)" ::: "memory");
.Lsp5_h:
	s_cmpk_eq_i32 s36, 0x100
	s_cbranch_scc0 .Lsp5_h2
	s_mov_b64 exec, 1
	s_lshl_b32 s98, s33, 8
	s_add_u32 s98, s98, 0x82400
	v_mov_b32_e32 v246, s98
	global_load_dword v247, v246, s[68:69] sc1
	s_mov_b64 exec, -1
	s_branch .Lsp5_back
.Lsp5_h2:
	s_cmpk_eq_i32 s36, 0x200
	s_cbranch_scc0 .Lsp5_back
	s_mov_b64 exec, 1
	s_mov_b32 s98, 0x40000

; #define PG8_STAGE(bufoff, gbase, voff) do { _Pragma("unroll") for (int _i = 0; _i < 2; ++_i) \
;         __builtin_amdgcn_global_load_lds((const unsigned*)((const char*)(gbase) + (voff)[_i]), (PG8_LAS unsigned*)(lds + (bufoff) + ldsw + _i * 8192), 16, 0, 0); } while (0)
; #define PG8_STAGEA(bufoff, gbase, voff) do { _Pragma("unroll") for (int _i = 0; _i < 2; ++_i) \
;         __builtin_amdgcn_global_load_lds((const unsigned*)((const char*)(gbase) + (voff)[_i]), (PG8_LAS unsigned*)(lds + (bufoff) + ldsw + _i * 8192), 16, 0, AUXA); } while (0)
; #define PG8_LDA(dst, b, h) do { _Pragma("unroll") for (int m = 0; m < 4; ++m) _Pragma("unroll") for (int k = 0; k < 2; ++k) dst[m][k] = *(const PG8_LAS bf16x8*)(lds + PG8_SA(b, h) + aoff + m * 2048 + k * 1024); } while (0)
; #define PG8_LDB(dst, b, h) do { _Pragma("unroll") for (int n = 0; n < 2; ++n) _Pragma("unroll") for (int k = 0; k < 2; ++k) dst[n][k] = *(const PG8_LAS bf16x8*)(lds + PG8_SB(b, h) + boff + n * 2048 + k * 1024); } while (0)
; #define PG8_MMA(ai, bj, At, Bt) do { __builtin_amdgcn_s_setprio(1); _Pragma("unroll") for (int m = 0; m < 4; ++m) _Pragma("unroll") for (int n = 0; n < 2; ++n) _Pragma("unroll") for (int k = 0; k < 2; ++k) \
;         acc[ai][bj][m][n] = __builtin_amdgcn_mfma_f32_16x16x32_bf16(Bt[n][k], At[m][k], acc[ai][bj][m][n], 0, 0, 0); __builtin_amdgcn_s_setprio(0); } while (0)
; #define PG8_WAIT_V(n) asm volatile("s_waitcnt vmcnt(" #n ")" ::: "memory")
; #define PG8_WAIT_L(n) asm volatile("s_waitcnt lgkmcnt(" #n ")" ::: "memory")
; #define PG8_BAR __builtin_amdgcn_s_barrier()
; #define PG8_SCHED __builtin_amdgcn_sched_barrier(0)
;     ...
;             PG8_LDB(B0, 0, 0); PG8_LDB(B1, 0, 1); PG8_SCHED; PG8_LDA(At, 0, 0); PG8_STAGEA(PG8_SA(1, 1), a1 + hstep, voffA);
;             PG8_WAIT_V(8); PG8_WAIT_L(0); PG8_BAR; PG8_MMA(0, 0, At, B0); PG8_MMA(0, 1, At, B1); PG8_BAR; PG8_SCHED;
;             PG8_LDA(At, 0, 1); PG8_STAGE(PG8_SB(0, 0), b2, voffB); PG8_STAGE(PG8_SB(0, 1), b2 + hstepB, voffB); PG8_STAGEA(PG8_SA(0, 0), a2, voffA);
;             PG8_WAIT_V(8); PG8_WAIT_L(0); PG8_BAR; PG8_MMA(1, 0, At, B0); PG8_MMA(1, 1, At, B1); PG8_BAR; PG8_SCHED;
.Lsprio_4:
.LBB0_888:
	v_add_u32_e32 v162, s12, v148
	v_add_u32_e32 v174, s50, v148
	s_add_u32 s38, s34, s36
	ds_read_b128 v[150:153], v162
	ds_read_b128 v[154:157], v162 offset:1024
	ds_read_b128 v[158:161], v162 offset:2048
	ds_read_b128 v[162:165], v162 offset:3072
	ds_read_b128 v[166:169], v174
	ds_read_b128 v[170:173], v174 offset:1024
	ds_read_b128 v[176:179], v174 offset:2048
	ds_read_b128 v[180:183], v174 offset:3072
	s_addc_u32 s39, s35, s37
	s_add_u32 s38, s38, 0x100
	s_addc_u32 s39, s39, 0
	s_add_u32 s59, s54, s36
	s_addc_u32 s70, s55, s37
	s_cmpk_eq_i32 s36, 0x700
	s_cselect_b32 s41, s27, s39
	s_cselect_b32 s40, s56, s38
	s_cselect_b32 s39, s25, s70
	s_cselect_b32 s38, s57, s59
	s_cmp_eq_u32 s101, 0x5555
	s_cbranch_scc1 .Lsp5_h
.Lsp5_back:
	v_lshl_add_u64 v[206:207], v[142:143], 0, s[36:37]
	s_add_i32 m0, s17, 0xc000
	ds_read_b128 v[184:187], v149
	ds_read_b128 v[188:191], v149 offset:1024
	ds_read_b128 v[192:195], v149 offset:2048
	ds_read_b128 v[196:199], v149 offset:3072
	ds_read_b128 v[202:205], v149 offset:4096
	ds_read_b128 v[210:213], v149 offset:5120
	ds_read_b128 v[214:217], v149 offset:6144
	ds_read_b128 v[218:221], v149 offset:7168
	global_load_lds_dwordx4 v[206:207], off
	v_lshl_add_u64 v[206:207], v[144:145], 0, s[36:37]
	s_add_i32 m0, s17, 0xe000
	s_nop 0
	global_load_lds_dwordx4 v[206:207], off
	s_waitcnt vmcnt(8)
	s_waitcnt lgkmcnt(0)
	s_barrier
	s_waitcnt lgkmcnt(0)
	v_mfma_f32_16x16x32_bf16 v[124:127], v[150:153], v[184:187], v[124:127]
	v_mfma_f32_16x16x32_bf16 v[120:123], v[158:161], v[184:187], v[120:123]
	v_mfma_f32_16x16x32_bf16 v[108:111], v[150:153], v[192:195], v[108:111]
	v_mfma_f32_16x16x32_bf16 v[104:107], v[158:161], v[192:195], v[104:107]
	v_mfma_f32_16x16x32_bf16 v[92:95], v[150:153], v[202:205], v[92:95]
	v_mfma_f32_16x16x32_bf16 v[88:91], v[158:161], v[202:205], v[88:91]
	v_mfma_f32_16x16x32_bf16 v[76:79], v[150:153], v[214:217], v[76:79]
	v_mfma_f32_16x16x32_bf16 v[72:75], v[158:161], v[214:217], v[72:75]
	v_mfma_f32_16x16x32_bf16 v[124:127], v[154:157], v[188:191], v[124:127]
	v_mfma_f32_16x16x32_bf16 v[120:123], v[162:165], v[188:191], v[120:123]
	v_mfma_f32_16x16x32_bf16 v[108:111], v[154:157], v[196:199], v[108:111]
	v_mfma_f32_16x16x32_bf16 v[104:107], v[162:165], v[196:199], v[104:107]
	v_mfma_f32_16x16x32_bf16 v[92:95], v[154:157], v[210:213], v[92:95]
	v_mfma_f32_16x16x32_bf16 v[88:91], v[162:165], v[210:213], v[88:91]
	v_mfma_f32_16x16x32_bf16 v[76:79], v[154:157], v[218:221], v[76:79]
	v_mfma_f32_16x16x32_bf16 v[72:75], v[162:165], v[218:221], v[72:75]
	v_mfma_f32_16x16x32_bf16 v[116:119], v[166:169], v[184:187], v[116:119]
	v_mfma_f32_16x16x32_bf16 v[112:115], v[176:179], v[184:187], v[112:115]
	v_mfma_f32_16x16x32_bf16 v[100:103], v[166:169], v[192:195], v[100:103]
	v_mfma_f32_16x16x32_bf16 v[96:99], v[176:179], v[192:195], v[96:99]
	v_mfma_f32_16x16x32_bf16 v[84:87], v[166:169], v[202:205], v[84:87]
	v_mfma_f32_16x16x32_bf16 v[80:83], v[176:179], v[202:205], v[80:83]
	v_mfma_f32_16x16x32_bf16 v[68:71], v[166:169], v[214:217], v[68:71]
	v_mfma_f32_16x16x32_bf16 v[64:67], v[176:179], v[214:217], v[64:67]
	v_mfma_f32_16x16x32_bf16 v[116:119], v[170:173], v[188:191], v[116:119]
	v_mfma_f32_16x16x32_bf16 v[112:115], v[180:183], v[188:191], v[112:115]
	v_mfma_f32_16x16x32_bf16 v[100:103], v[170:173], v[196:199], v[100:103]
	v_mfma_f32_16x16x32_bf16 v[96:99], v[180:183], v[196:199], v[96:99]
	v_mfma_f32_16x16x32_bf16 v[84:87], v[170:173], v[210:213], v[84:87]
	v_mfma_f32_16x16x32_bf16 v[80:83], v[180:183], v[210:213], v[80:83]
	v_mfma_f32_16x16x32_bf16 v[68:71], v[170:173], v[218:221], v[68:71]
	v_mfma_f32_16x16x32_bf16 v[64:67], v[180:183], v[218:221], v[64:67]
	s_barrier
	s_add_i32 s59, s12, s67
	v_lshl_add_u64 v[206:207], s[38:39], 0, v[132:133]
	s_mov_b32 m0, s59
	ds_read_b128 v[184:187], v149 offset:16384
	ds_read_b128 v[188:191], v149 offset:17408
	ds_read_b128 v[192:195], v149 offset:18432
	ds_read_b128 v[196:199], v149 offset:19456
	ds_read_b128 v[202:205], v149 offset:20480
	ds_read_b128 v[210:213], v149 offset:21504
	ds_read_b128 v[214:217], v149 offset:22528
	ds_read_b128 v[218:221], v149 offset:23552
	global_load_lds_dwordx4 v[206:207], off
	s_add_i32 m0, s59, 0x2000
	s_add_u32 s70, s38, 0x10000
	v_lshl_add_u64 v[222:223], s[38:39], 0, v[128:129]
	s_addc_u32 s71, s39, 0
	s_add_i32 s59, s50, s67
	global_load_lds_dwordx4 v[222:223], off
	v_lshl_add_u64 v[224:225], s[70:71], 0, v[132:133]
	s_mov_b32 m0, s59
	v_lshl_add_u64 v[226:227], s[40:41], 0, v[130:131]
	global_load_lds_dwordx4 v[224:225], off
	v_lshl_add_u64 v[224:225], s[70:71], 0, v[128:129]
	s_add_i32 m0, s59, 0x2000
	s_nop 0
	global_load_lds_dwordx4 v[224:225], off
	v_lshl_add_u64 v[224:225], s[40:41], 0, v[134:135]
	s_mov_b32 m0, s17
	s_nop 0
	global_load_lds_dwordx4 v[224:225], off
	s_mov_b32 m0, s43
	s_nop 0
	global_load_lds_dwordx4 v[226:227], off
	s_waitcnt vmcnt(8)
	s_waitcnt lgkmcnt(0)
	s_barrier
; #define PG8_STAGEA(bufoff, gbase, voff) do { _Pragma("unroll") for (int _i = 0; _i < 2; ++_i) \
;         __builtin_amdgcn_global_load_lds((const unsigned*)((const char*)(gbase) + (voff)[_i]), (PG8_LAS unsigned*)(lds + (bufoff) + ldsw + _i * 8192), 16, 0, AUXA); } while (0)
; #define PG8_LDA(dst, b, h) do { _Pragma("unroll") for (int m = 0; m < 4; ++m) _Pragma("unroll") for (int k = 0; k < 2; ++k) dst[m][k] = *(const PG8_LAS bf16x8*)(lds + PG8_SA(b, h) + aoff + m * 2048 + k * 1024); } while (0)
; #define PG8_LDB(dst, b, h) do { _Pragma("unroll") for (int n = 0; n < 2; ++n) _Pragma("unroll") for (int k = 0; k < 2; ++k) dst[n][k] = *(const PG8_LAS bf16x8*)(lds + PG8_SB(b, h) + boff + n * 2048 + k * 1024); } while (0)
; #define PG8_MMA(ai, bj, At, Bt) do { __builtin_amdgcn_s_setprio(1); _Pragma("unroll") for (int m = 0; m < 4; ++m) _Pragma("unroll") for (int n = 0; n < 2; ++n) _Pragma("unroll") for (int k = 0; k < 2; ++k) \
;         acc[ai][bj][m][n] = __builtin_amdgcn_mfma_f32_16x16x32_bf16(Bt[n][k], At[m][k], acc[ai][bj][m][n], 0, 0, 0); __builtin_amdgcn_s_setprio(0); } while (0)
; #define PG8_WAIT_V(n) asm volatile("s_waitcnt vmcnt(" #n ")" ::: "memory")
; #define PG8_WAIT_L(n) asm volatile("s_waitcnt lgkmcnt(" #n ")" ::: "memory")
; #define PG8_BAR __builtin_amdgcn_s_barrier()
; #define PG8_SCHED __builtin_amdgcn_sched_barrier(0)
;     ...
;             PG8_WAIT_V(8); PG8_WAIT_L(0); PG8_BAR; PG8_MMA(1, 0, At, B0); PG8_MMA(1, 1, At, B1); PG8_BAR; PG8_SCHED;
;             PG8_LDB(B0, 1, 0); PG8_LDB(B1, 1, 1); PG8_SCHED; PG8_LDA(At, 1, 0); PG8_STAGEA(PG8_SA(0, 1), a2 + hstep, voffA);
;             PG8_WAIT_V(8); PG8_WAIT_L(0); PG8_BAR; PG8_MMA(0, 0, At, B0); PG8_MMA(0, 1, At, B1); PG8_BAR; PG8_SCHED;
	s_waitcnt lgkmcnt(0)
	v_mfma_f32_16x16x32_bf16 v[60:63], v[150:153], v[184:187], v[60:63]
	v_mfma_f32_16x16x32_bf16 v[56:59], v[158:161], v[184:187], v[56:59]
	v_mfma_f32_16x16x32_bf16 v[44:47], v[150:153], v[192:195], v[44:47]
	v_mfma_f32_16x16x32_bf16 v[40:43], v[158:161], v[192:195], v[40:43]
	v_mfma_f32_16x16x32_bf16 v[28:31], v[150:153], v[202:205], v[28:31]
	v_mfma_f32_16x16x32_bf16 v[24:27], v[158:161], v[202:205], v[24:27]
	v_mfma_f32_16x16x32_bf16 v[12:15], v[150:153], v[214:217], v[12:15]
	v_mfma_f32_16x16x32_bf16 v[8:11], v[158:161], v[214:217], v[8:11]
	v_mfma_f32_16x16x32_bf16 v[60:63], v[154:157], v[188:191], v[60:63]
	v_mfma_f32_16x16x32_bf16 v[56:59], v[162:165], v[188:191], v[56:59]
	v_mfma_f32_16x16x32_bf16 v[44:47], v[154:157], v[196:199], v[44:47]
	v_mfma_f32_16x16x32_bf16 v[40:43], v[162:165], v[196:199], v[40:43]
	v_mfma_f32_16x16x32_bf16 v[28:31], v[154:157], v[210:213], v[28:31]
	v_mfma_f32_16x16x32_bf16 v[24:27], v[162:165], v[210:213], v[24:27]
	v_mfma_f32_16x16x32_bf16 v[12:15], v[154:157], v[218:221], v[12:15]
	v_mfma_f32_16x16x32_bf16 v[8:11], v[162:165], v[218:221], v[8:11]
	v_mfma_f32_16x16x32_bf16 v[52:55], v[166:169], v[184:187], v[52:55]
	v_mfma_f32_16x16x32_bf16 v[48:51], v[176:179], v[184:187], v[48:51]
	v_mfma_f32_16x16x32_bf16 v[36:39], v[166:169], v[192:195], v[36:39]
	v_mfma_f32_16x16x32_bf16 v[32:35], v[176:179], v[192:195], v[32:35]
	v_mfma_f32_16x16x32_bf16 v[20:23], v[166:169], v[202:205], v[20:23]
	v_mfma_f32_16x16x32_bf16 v[16:19], v[176:179], v[202:205], v[16:19]
	v_mfma_f32_16x16x32_bf16 v[4:7], v[166:169], v[214:217], v[4:7]
	v_mfma_f32_16x16x32_bf16 v[0:3], v[176:179], v[214:217], v[0:3]
	v_mfma_f32_16x16x32_bf16 v[52:55], v[170:173], v[188:191], v[52:55]
	v_mfma_f32_16x16x32_bf16 v[48:51], v[180:183], v[188:191], v[48:51]
	v_mfma_f32_16x16x32_bf16 v[36:39], v[170:173], v[196:199], v[36:39]
	v_mfma_f32_16x16x32_bf16 v[32:35], v[180:183], v[196:199], v[32:35]
	v_mfma_f32_16x16x32_bf16 v[20:23], v[170:173], v[210:213], v[20:23]
	v_mfma_f32_16x16x32_bf16 v[16:19], v[180:183], v[210:213], v[16:19]
	v_mfma_f32_16x16x32_bf16 v[4:7], v[170:173], v[218:221], v[4:7]
	v_mfma_f32_16x16x32_bf16 v[0:3], v[180:183], v[218:221], v[0:3]
	s_barrier
	s_add_i32 s59, 0, 0x18000
	s_add_i32 s70, 0, 0x1c000
	v_add_u32_e32 v162, s59, v148
	v_add_u32_e32 v174, s70, v148
	ds_read_b128 v[150:153], v162
	ds_read_b128 v[154:157], v162 offset:1024
	ds_read_b128 v[158:161], v162 offset:2048
	ds_read_b128 v[162:165], v162 offset:3072
	ds_read_b128 v[166:169], v174
	ds_read_b128 v[170:173], v174 offset:1024
	ds_read_b128 v[176:179], v174 offset:2048
	ds_read_b128 v[180:183], v174 offset:3072
	s_add_u32 s40, s40, 0x40000
	s_addc_u32 s41, s41, 0
	s_mov_b32 m0, s44
	v_lshl_add_u64 v[228:229], s[40:41], 0, v[134:135]
	ds_read_b128 v[184:187], v149 offset:32768
	ds_read_b128 v[188:191], v149 offset:33792
	ds_read_b128 v[192:195], v149 offset:34816
	ds_read_b128 v[196:199], v149 offset:35840
	ds_read_b128 v[202:205], v149 offset:36864
	ds_read_b128 v[210:213], v149 offset:37888
	ds_read_b128 v[214:217], v149 offset:38912
	ds_read_b128 v[218:221], v149 offset:39936
	global_load_lds_dwordx4 v[228:229], off
	v_lshl_add_u64 v[228:229], s[40:41], 0, v[130:131]
	s_mov_b32 m0, s45
	s_nop 0
	global_load_lds_dwordx4 v[228:229], off
	s_waitcnt vmcnt(8)
	s_waitcnt lgkmcnt(0)
	s_barrier
	s_waitcnt lgkmcnt(0)
	v_mfma_f32_16x16x32_bf16 v[124:127], v[150:153], v[184:187], v[124:127]
	v_mfma_f32_16x16x32_bf16 v[120:123], v[158:161], v[184:187], v[120:123]
	v_mfma_f32_16x16x32_bf16 v[108:111], v[150:153], v[192:195], v[108:111]
	v_mfma_f32_16x16x32_bf16 v[104:107], v[158:161], v[192:195], v[104:107]
	v_mfma_f32_16x16x32_bf16 v[92:95], v[150:153], v[202:205], v[92:95]
	v_mfma_f32_16x16x32_bf16 v[88:91], v[158:161], v[202:205], v[88:91]
	v_mfma_f32_16x16x32_bf16 v[76:79], v[150:153], v[214:217], v[76:79]
	v_mfma_f32_16x16x32_bf16 v[72:75], v[158:161], v[214:217], v[72:75]
	v_mfma_f32_16x16x32_bf16 v[124:127], v[154:157], v[188:191], v[124:127]
	v_mfma_f32_16x16x32_bf16 v[120:123], v[162:165], v[188:191], v[120:123]
	v_mfma_f32_16x16x32_bf16 v[108:111], v[154:157], v[196:199], v[108:111]
	v_mfma_f32_16x16x32_bf16 v[104:107], v[162:165], v[196:199], v[104:107]
	v_mfma_f32_16x16x32_bf16 v[92:95], v[154:157], v[210:213], v[92:95]
	v_mfma_f32_16x16x32_bf16 v[88:91], v[162:165], v[210:213], v[88:91]
	v_mfma_f32_16x16x32_bf16 v[76:79], v[154:157], v[218:221], v[76:79]
	v_mfma_f32_16x16x32_bf16 v[72:75], v[162:165], v[218:221], v[72:75]
	v_mfma_f32_16x16x32_bf16 v[116:119], v[166:169], v[184:187], v[116:119]
	v_mfma_f32_16x16x32_bf16 v[112:115], v[176:179], v[184:187], v[112:115]
	v_mfma_f32_16x16x32_bf16 v[100:103], v[166:169], v[192:195], v[100:103]
	v_mfma_f32_16x16x32_bf16 v[96:99], v[176:179], v[192:195], v[96:99]
	v_mfma_f32_16x16x32_bf16 v[84:87], v[166:169], v[202:205], v[84:87]
	v_mfma_f32_16x16x32_bf16 v[80:83], v[176:179], v[202:205], v[80:83]
	v_mfma_f32_16x16x32_bf16 v[68:71], v[166:169], v[214:217], v[68:71]
	v_mfma_f32_16x16x32_bf16 v[64:67], v[176:179], v[214:217], v[64:67]
	v_mfma_f32_16x16x32_bf16 v[116:119], v[170:173], v[188:191], v[116:119]
	v_mfma_f32_16x16x32_bf16 v[112:115], v[180:183], v[188:191], v[112:115]
	v_mfma_f32_16x16x32_bf16 v[100:103], v[170:173], v[196:199], v[100:103]
	v_mfma_f32_16x16x32_bf16 v[96:99], v[180:183], v[196:199], v[96:99]
	v_mfma_f32_16x16x32_bf16 v[84:87], v[170:173], v[210:213], v[84:87]
	v_mfma_f32_16x16x32_bf16 v[80:83], v[180:183], v[210:213], v[80:83]
	v_mfma_f32_16x16x32_bf16 v[68:71], v[170:173], v[218:221], v[68:71]
	v_mfma_f32_16x16x32_bf16 v[64:67], v[180:183], v[218:221], v[64:67]
	s_barrier
; #define PG8_STAGE(bufoff, gbase, voff) do { _Pragma("unroll") for (int _i = 0; _i < 2; ++_i) \
;         __builtin_amdgcn_global_load_lds((const unsigned*)((const char*)(gbase) + (voff)[_i]), (PG8_LAS unsigned*)(lds + (bufoff) + ldsw + _i * 8192), 16, 0, 0); } while (0)
; #define PG8_WAIT_V(n) asm volatile("s_waitcnt vmcnt(" #n ")" ::: "memory")
; #define PG8_WAIT_L(n) asm volatile("s_waitcnt lgkmcnt(" #n ")" ::: "memory")
; #define PG8_BAR __builtin_amdgcn_s_barrier()
;     ...
;             PG8_WAIT_V(8); PG8_WAIT_L(0); PG8_BAR; PG8_MMA(0, 0, At, B0); PG8_MMA(0, 1, At, B1); PG8_BAR; PG8_SCHED;
;             PG8_LDA(At, 1, 1); PG8_STAGE(PG8_SB(1, 0), b3, voffB); PG8_STAGE(PG8_SB(1, 1), b3 + hstepB, voffB); PG8_STAGEA(PG8_SA(1, 0), a3, voffA);
;             PG8_WAIT_V(8); PG8_WAIT_L(0); PG8_BAR; PG8_MMA(1, 0, At, B0); PG8_MMA(1, 1, At, B1); PG8_BAR; PG8_SCHED;
;             } else {
;             PG8_LDB(B0, 0, 0); PG8_SCHED; PG8_LDA(At, 0, 0); PG8_STAGEA(PG8_SA(1, 1), a1 + hstep, voffA);
;             PG8_WAIT_L(8); PG8_BAR; PG8_WAIT_L(0); PG8_MMA(0, 0, At, B0); PG8_BAR; PG8_SCHED;
;             PG8_LDB(B1, 0, 1); PG8_STAGE(PG8_SB(0, 0), b2, voffB);
;             PG8_BAR; PG8_WAIT_L(0); PG8_MMA(0, 1, At, B1); PG8_BAR;
;             PG8_LDA(At, 0, 1); PG8_STAGEA(PG8_SA(0, 0), a2, voffA);
;             PG8_BAR; PG8_WAIT_L(0); PG8_MMA(1, 0, At, B0); PG8_BAR; PG8_SCHED;
;             PG8_STAGE(PG8_SB(0, 1), b2 + hstepB, voffB);
;             PG8_WAIT_V(6); PG8_BAR; PG8_MMA(1, 1, At, B1); PG8_BAR;
;             PG8_LDB(B0, 1, 0); PG8_SCHED; PG8_LDA(At, 1, 0); PG8_STAGEA(PG8_SA(0, 1), a2 + hstep, voffA);
;             PG8_WAIT_L(8); PG8_BAR; PG8_WAIT_L(0); PG8_MMA(0, 0, At, B0); PG8_BAR; PG8_SCHED;
;             PG8_LDB(B1, 1, 1); PG8_STAGE(PG8_SB(1, 0), b3, voffB);
;             PG8_BAR; PG8_WAIT_L(0); PG8_MMA(0, 1, At, B1); PG8_BAR;
;             PG8_LDA(At, 1, 1); PG8_STAGEA(PG8_SA(1, 0), a3, voffA);
;             PG8_BAR; PG8_WAIT_L(0); PG8_MMA(1, 0, At, B0); PG8_BAR; PG8_SCHED;
;             PG8_STAGE(PG8_SB(1, 1), b3 + hstepB, voffB);
;             PG8_WAIT_V(6); PG8_BAR; PG8_MMA(1, 1, At, B1); PG8_BAR;
;             }
;         }
;         if constexpr (ALIGN_EPI) { if (wr == 0) PG8_BAR; }
;         if constexpr (!Epi::AFTER_DRAIN) { if (!(Epi::LAST_FUSED && !has_next)) { E(acc, cur, wr, wc, fr, fq); S.done(cur); } }
;         if (!has_next) break;
	s_add_i32 s40, s59, s67
	v_lshl_add_u64 v[206:207], v[206:207], 0, s[20:21]
	s_mov_b32 m0, s40
	ds_read_b128 v[184:187], v149 offset:49152
	ds_read_b128 v[188:191], v149 offset:50176
	ds_read_b128 v[192:195], v149 offset:51200
	ds_read_b128 v[196:199], v149 offset:52224
	ds_read_b128 v[202:205], v149 offset:53248
	ds_read_b128 v[210:213], v149 offset:54272
	ds_read_b128 v[214:217], v149 offset:55296
	ds_read_b128 v[218:221], v149 offset:56320
	global_load_lds_dwordx4 v[206:207], off
	s_add_i32 m0, s40, 0x2000
	s_add_u32 s38, s38, 0x10080
	v_lshl_add_u64 v[206:207], v[222:223], 0, s[20:21]
	s_addc_u32 s39, s39, 0
	s_add_i32 s40, s70, s67
	global_load_lds_dwordx4 v[206:207], off
	v_lshl_add_u64 v[206:207], s[38:39], 0, v[132:133]
	s_mov_b32 m0, s40
	s_nop 0
	global_load_lds_dwordx4 v[206:207], off
	v_lshl_add_u64 v[206:207], s[38:39], 0, v[128:129]
	s_add_i32 m0, s40, 0x2000
	s_nop 0
	global_load_lds_dwordx4 v[206:207], off
	v_lshl_add_u64 v[206:207], v[224:225], 0, s[20:21]
	s_mov_b32 m0, s46
	s_nop 0
	global_load_lds_dwordx4 v[206:207], off
	v_lshl_add_u64 v[206:207], v[226:227], 0, s[20:21]
	s_mov_b32 m0, s47
	s_nop 0
	global_load_lds_dwordx4 v[206:207], off
	s_waitcnt vmcnt(8)
	s_waitcnt lgkmcnt(0)
	s_barrier
	s_waitcnt lgkmcnt(0)
	v_mfma_f32_16x16x32_bf16 v[60:63], v[150:153], v[184:187], v[60:63]
	v_mfma_f32_16x16x32_bf16 v[56:59], v[158:161], v[184:187], v[56:59]
	v_mfma_f32_16x16x32_bf16 v[44:47], v[150:153], v[192:195], v[44:47]
	v_mfma_f32_16x16x32_bf16 v[40:43], v[158:161], v[192:195], v[40:43]
	v_mfma_f32_16x16x32_bf16 v[28:31], v[150:153], v[202:205], v[28:31]
	v_mfma_f32_16x16x32_bf16 v[24:27], v[158:161], v[202:205], v[24:27]
	v_mfma_f32_16x16x32_bf16 v[12:15], v[150:153], v[214:217], v[12:15]
	v_mfma_f32_16x16x32_bf16 v[8:11], v[158:161], v[214:217], v[8:11]
	v_mfma_f32_16x16x32_bf16 v[60:63], v[154:157], v[188:191], v[60:63]
	v_mfma_f32_16x16x32_bf16 v[56:59], v[162:165], v[188:191], v[56:59]
	v_mfma_f32_16x16x32_bf16 v[44:47], v[154:157], v[196:199], v[44:47]
	v_mfma_f32_16x16x32_bf16 v[40:43], v[162:165], v[196:199], v[40:43]
	v_mfma_f32_16x16x32_bf16 v[28:31], v[154:157], v[210:213], v[28:31]
	v_mfma_f32_16x16x32_bf16 v[24:27], v[162:165], v[210:213], v[24:27]
	v_mfma_f32_16x16x32_bf16 v[12:15], v[154:157], v[218:221], v[12:15]
	v_mfma_f32_16x16x32_bf16 v[8:11], v[162:165], v[218:221], v[8:11]
	v_mfma_f32_16x16x32_bf16 v[52:55], v[166:169], v[184:187], v[52:55]
	v_mfma_f32_16x16x32_bf16 v[48:51], v[176:179], v[184:187], v[48:51]
	v_mfma_f32_16x16x32_bf16 v[36:39], v[166:169], v[192:195], v[36:39]
	v_mfma_f32_16x16x32_bf16 v[32:35], v[176:179], v[192:195], v[32:35]
	v_mfma_f32_16x16x32_bf16 v[20:23], v[166:169], v[202:205], v[20:23]
	v_mfma_f32_16x16x32_bf16 v[16:19], v[176:179], v[202:205], v[16:19]
	v_mfma_f32_16x16x32_bf16 v[4:7], v[166:169], v[214:217], v[4:7]
	v_mfma_f32_16x16x32_bf16 v[0:3], v[176:179], v[214:217], v[0:3]
	v_mfma_f32_16x16x32_bf16 v[52:55], v[170:173], v[188:191], v[52:55]
	v_mfma_f32_16x16x32_bf16 v[48:51], v[180:183], v[188:191], v[48:51]
	v_mfma_f32_16x16x32_bf16 v[36:39], v[170:173], v[196:199], v[36:39]
	v_mfma_f32_16x16x32_bf16 v[32:35], v[180:183], v[196:199], v[32:35]
	v_mfma_f32_16x16x32_bf16 v[20:23], v[170:173], v[210:213], v[20:23]
	v_mfma_f32_16x16x32_bf16 v[16:19], v[180:183], v[210:213], v[16:19]
	v_mfma_f32_16x16x32_bf16 v[4:7], v[170:173], v[218:221], v[4:7]
	v_mfma_f32_16x16x32_bf16 v[0:3], v[180:183], v[218:221], v[0:3]
	s_barrier
	s_add_i32 s58, s58, 2
	s_add_u32 s36, s36, 0x100
	s_addc_u32 s37, s37, 0
	s_cmp_gt_u32 s58, 13
	s_cbranch_scc0 .LBB0_888
	s_setprio 0
	s_and_b64 vcc, exec, s[22:23]
	s_cbranch_vccz .LBB0_891
	s_barrier
